# v013 K-loop trims + accumulator clear with 64 v_mov_b64 per GEMM unit instead of 128 v_mov_b32
# speedup vs baseline: 1.0075x; 1.0052x over previous
.LBB0_269:
	s_ashr_i32 s25, s24, 31
	s_lshl_b64 s[26:27], s[24:25], 20
	s_add_u32 s26, s36, s26
	s_addc_u32 s27, s37, s27
	s_and_b64 s[28:29], s[6:7], exec
	s_cselect_b32 s2, s27, s31
	s_cselect_b32 s25, s26, s30
	s_ashr_i32 s23, s22, 31
	s_lshl_b64 s[28:29], s[22:23], 20
	s_add_u32 s28, s38, s28
	s_addc_u32 s29, s39, s29
	s_and_b64 s[34:35], s[6:7], exec
	s_cselect_b32 s23, s29, s57
	s_cselect_b32 s54, s28, s56
	s_ashr_i32 s1, s0, 31
	s_lshl_b64 s[34:35], s[0:1], 13
	s_add_u32 s1, s56, 0x100
	s_addc_u32 s55, s57, 0
	s_add_u32 s8, s30, 0x80080
	v_mov_b64_e32 v[2:3], 0
	s_waitcnt vmcnt(0)
	v_lshl_add_u64 v[66:67], v[168:169], 0, s[34:35]
	s_addc_u32 s9, s31, 0
	s_mov_b32 s56, -2
	v_mov_b64_e32 v[4:5], 0
	v_mov_b64_e32 v[6:7], 0
	v_mov_b64_e32 v[8:9], 0
	v_mov_b64_e32 v[18:19], 0
	v_mov_b64_e32 v[20:21], 0
	v_mov_b64_e32 v[22:23], 0
	v_mov_b64_e32 v[24:25], 0
	v_mov_b64_e32 v[34:35], 0
	v_mov_b64_e32 v[36:37], 0
	v_mov_b64_e32 v[38:39], 0
	v_mov_b64_e32 v[40:41], 0
	v_mov_b64_e32 v[50:51], 0
	v_mov_b64_e32 v[52:53], 0
	v_mov_b64_e32 v[54:55], 0
	v_mov_b64_e32 v[56:57], 0
	v_mov_b64_e32 v[10:11], 0
	v_mov_b64_e32 v[12:13], 0
	v_mov_b64_e32 v[14:15], 0
	v_mov_b64_e32 v[16:17], 0
	v_mov_b64_e32 v[26:27], 0
	v_mov_b64_e32 v[28:29], 0
	v_mov_b64_e32 v[30:31], 0
	v_mov_b64_e32 v[32:33], 0
	v_mov_b64_e32 v[42:43], 0
	v_mov_b64_e32 v[44:45], 0
	v_mov_b64_e32 v[46:47], 0
	v_mov_b64_e32 v[48:49], 0
	v_mov_b64_e32 v[58:59], 0
	v_mov_b64_e32 v[60:61], 0
	v_mov_b64_e32 v[62:63], 0
	v_mov_b64_e32 v[64:65], 0
	v_mov_b64_e32 v[74:75], 0
	v_mov_b64_e32 v[76:77], 0
	v_mov_b64_e32 v[78:79], 0
	v_mov_b64_e32 v[80:81], 0
	v_mov_b64_e32 v[98:99], 0
	v_mov_b64_e32 v[100:101], 0
	v_mov_b64_e32 v[102:103], 0
	v_mov_b64_e32 v[104:105], 0
	v_mov_b64_e32 v[114:115], 0
	v_mov_b64_e32 v[116:117], 0
	v_mov_b64_e32 v[118:119], 0
	v_mov_b64_e32 v[120:121], 0
	v_mov_b64_e32 v[130:131], 0
	v_mov_b64_e32 v[132:133], 0
	v_mov_b64_e32 v[134:135], 0
	v_mov_b64_e32 v[136:137], 0
	v_mov_b64_e32 v[90:91], 0
	v_mov_b64_e32 v[92:93], 0
	v_mov_b64_e32 v[94:95], 0
	v_mov_b64_e32 v[96:97], 0
	v_mov_b64_e32 v[106:107], 0
	v_mov_b64_e32 v[108:109], 0
	v_mov_b64_e32 v[110:111], 0
	v_mov_b64_e32 v[112:113], 0
	v_mov_b64_e32 v[122:123], 0
	v_mov_b64_e32 v[124:125], 0
	v_mov_b64_e32 v[126:127], 0
	v_mov_b64_e32 v[128:129], 0
	v_mov_b64_e32 v[138:139], 0
	v_mov_b64_e32 v[140:141], 0
	v_mov_b64_e32 v[142:143], 0
	v_mov_b64_e32 v[144:145], 0
	s_branch .LBB0_271

.LBB0_616:
	s_ashr_i32 s27, s26, 31
	s_lshl_b64 s[28:29], s[26:27], 20
	s_add_u32 s28, s2, s28
	s_addc_u32 s29, s38, s29
	s_and_b64 s[30:31], s[6:7], exec
	s_cselect_b32 s21, s29, s35
	s_cselect_b32 s23, s28, s34
	s_ashr_i32 s25, s24, 31
	s_lshl_b64 s[30:31], s[24:25], 20
	s_add_u32 s30, s39, s30
	s_addc_u32 s31, s40, s31
	s_and_b64 s[36:37], s[6:7], exec
	s_cselect_b32 s25, s31, s9
	s_cselect_b32 s27, s30, s8
	s_add_u32 s61, s8, 0x100
	s_addc_u32 s62, s9, 0
	s_add_u32 s8, s34, 0x80080
	v_mov_b64_e32 v[2:3], 0
	s_addc_u32 s9, s35, 0
	s_mov_b32 s63, -2
	v_mov_b64_e32 v[4:5], 0
	v_mov_b64_e32 v[6:7], 0
	v_mov_b64_e32 v[8:9], 0
	v_mov_b64_e32 v[18:19], 0
	v_mov_b64_e32 v[20:21], 0
	v_mov_b64_e32 v[22:23], 0
	v_mov_b64_e32 v[24:25], 0
	v_mov_b64_e32 v[34:35], 0
	v_mov_b64_e32 v[36:37], 0
	v_mov_b64_e32 v[38:39], 0
	v_mov_b64_e32 v[40:41], 0
	v_mov_b64_e32 v[50:51], 0
	v_mov_b64_e32 v[52:53], 0
	v_mov_b64_e32 v[54:55], 0
	v_mov_b64_e32 v[56:57], 0
	v_mov_b64_e32 v[10:11], 0
	v_mov_b64_e32 v[12:13], 0
	v_mov_b64_e32 v[14:15], 0
	v_mov_b64_e32 v[16:17], 0
	v_mov_b64_e32 v[26:27], 0
	v_mov_b64_e32 v[28:29], 0
	v_mov_b64_e32 v[30:31], 0
	v_mov_b64_e32 v[32:33], 0
	v_mov_b64_e32 v[42:43], 0
	v_mov_b64_e32 v[44:45], 0
	v_mov_b64_e32 v[46:47], 0
	v_mov_b64_e32 v[48:49], 0
	v_mov_b64_e32 v[58:59], 0
	v_mov_b64_e32 v[60:61], 0
	v_mov_b64_e32 v[62:63], 0
	v_mov_b64_e32 v[64:65], 0
	v_mov_b64_e32 v[82:83], 0
	v_mov_b64_e32 v[84:85], 0
	v_mov_b64_e32 v[86:87], 0
	v_mov_b64_e32 v[88:89], 0
	v_mov_b64_e32 v[98:99], 0
	v_mov_b64_e32 v[100:101], 0
	v_mov_b64_e32 v[102:103], 0
	v_mov_b64_e32 v[104:105], 0
	v_mov_b64_e32 v[118:119], 0
	v_mov_b64_e32 v[120:121], 0
	v_mov_b64_e32 v[122:123], 0
	v_mov_b64_e32 v[124:125], 0
	v_mov_b64_e32 v[114:115], 0
	v_mov_b64_e32 v[116:117], 0
	v_mov_b64_e32 v[126:127], 0
	v_mov_b64_e32 v[128:129], 0
	v_mov_b64_e32 v[90:91], 0
	v_mov_b64_e32 v[92:93], 0
	v_mov_b64_e32 v[94:95], 0
	v_mov_b64_e32 v[96:97], 0
	v_mov_b64_e32 v[106:107], 0
	v_mov_b64_e32 v[108:109], 0
	v_mov_b64_e32 v[110:111], 0
	v_mov_b64_e32 v[112:113], 0
	v_mov_b64_e32 v[134:135], 0
	v_mov_b64_e32 v[136:137], 0
	v_mov_b64_e32 v[138:139], 0
	v_mov_b64_e32 v[140:141], 0
	v_mov_b64_e32 v[150:151], 0
	v_mov_b64_e32 v[152:153], 0
	v_mov_b64_e32 v[154:155], 0
	v_mov_b64_e32 v[156:157], 0

.LBB0_742:
	s_ashr_i32 s31, s30, 31
	s_lshl_b64 s[12:13], s[30:31], 20
	s_add_u32 s34, s2, s12
	s_addc_u32 s35, s52, s13
	s_and_b64 s[12:13], s[10:11], exec
	s_cselect_b32 s31, s35, s39
	s_cselect_b32 s88, s34, s38
	s_ashr_i32 s29, s28, 31
	s_lshl_b64 s[12:13], s[28:29], 20
	s_add_u32 s36, s53, s12
	s_addc_u32 s37, s54, s13
	s_and_b64 s[12:13], s[10:11], exec
	s_cselect_b32 s29, s37, s45
	s_cselect_b32 s90, s36, s44
	s_ashr_i32 s41, s40, 31
	s_lshl_b64 s[12:13], s[40:41], 13
	s_ashr_i32 s41, s40, 5
	s_lshl_b32 s46, s42, 8
	s_lshl_b32 s42, s42, 7
	s_mul_hi_i32 s50, s41, 0xb000
	s_mul_i32 s41, s41, 0xb000
	s_ashr_i32 s47, s46, 31
	s_ashr_i32 s43, s42, 31
	s_add_u32 s41, s69, s41
	v_lshl_add_u64 v[66:67], v[170:171], 0, s[12:13]
	s_addc_u32 s50, s73, s50
	s_lshl_b64 s[12:13], s[46:47], 2
	s_add_u32 s41, s41, s12
	s_addc_u32 s46, s50, s13
	s_lshl_b64 s[12:13], s[42:43], 2
	s_add_u32 s43, s81, s12
	s_addc_u32 s47, s84, s13
	v_mov_b32_e32 v2, s46
	v_mov_b32_e32 v3, s47
	v_lshl_add_u64 v[70:71], v[172:173], 0, s[12:13]
	s_add_u32 s12, s41, 0x200
	v_cndmask_b32_e64 v69, v2, v3, s[14:15]
	v_mov_b32_e32 v2, s41
	v_mov_b32_e32 v3, s43
	s_addc_u32 s13, s46, 0
	v_cndmask_b32_e64 v68, v2, v3, s[14:15]
	s_add_u32 s41, s44, 0x100
	v_mov_b64_e32 v[2:3], 0
	s_addc_u32 s43, s45, 0
	s_mov_b32 s91, -2
	v_mov_b64_e32 v[4:5], 0
	v_mov_b64_e32 v[6:7], 0
	v_mov_b64_e32 v[8:9], 0
	v_mov_b64_e32 v[10:11], 0
	v_mov_b64_e32 v[12:13], 0
	v_mov_b64_e32 v[18:19], 0
	v_mov_b64_e32 v[20:21], 0
	v_mov_b64_e32 v[26:27], 0
	v_mov_b64_e32 v[28:29], 0
	v_mov_b64_e32 v[34:35], 0
	v_mov_b64_e32 v[36:37], 0
	v_mov_b64_e32 v[42:43], 0
	v_mov_b64_e32 v[44:45], 0
	v_mov_b64_e32 v[50:51], 0
	v_mov_b64_e32 v[52:53], 0
	v_mov_b64_e32 v[14:15], 0
	v_mov_b64_e32 v[16:17], 0
	v_mov_b64_e32 v[22:23], 0
	v_mov_b64_e32 v[24:25], 0
	v_mov_b64_e32 v[30:31], 0
	v_mov_b64_e32 v[32:33], 0
	v_mov_b64_e32 v[38:39], 0
	v_mov_b64_e32 v[40:41], 0
	v_mov_b64_e32 v[46:47], 0
	v_mov_b64_e32 v[48:49], 0
	v_mov_b64_e32 v[54:55], 0
	v_mov_b64_e32 v[56:57], 0
	v_mov_b64_e32 v[58:59], 0
	v_mov_b64_e32 v[60:61], 0
	v_mov_b64_e32 v[62:63], 0
	v_mov_b64_e32 v[64:65], 0
	v_mov_b64_e32 v[90:91], 0
	v_mov_b64_e32 v[92:93], 0
	v_mov_b64_e32 v[94:95], 0
	v_mov_b64_e32 v[96:97], 0
	v_mov_b64_e32 v[98:99], 0
	v_mov_b64_e32 v[100:101], 0
	v_mov_b64_e32 v[102:103], 0
	v_mov_b64_e32 v[104:105], 0
	v_mov_b64_e32 v[106:107], 0
	v_mov_b64_e32 v[108:109], 0
	v_mov_b64_e32 v[110:111], 0
	v_mov_b64_e32 v[112:113], 0
	v_mov_b64_e32 v[130:131], 0
	v_mov_b64_e32 v[132:133], 0
	v_mov_b64_e32 v[138:139], 0
	v_mov_b64_e32 v[140:141], 0
	v_mov_b64_e32 v[122:123], 0
	v_mov_b64_e32 v[124:125], 0
	v_mov_b64_e32 v[126:127], 0
	v_mov_b64_e32 v[128:129], 0
	v_mov_b64_e32 v[134:135], 0
	v_mov_b64_e32 v[136:137], 0
	v_mov_b64_e32 v[142:143], 0
	v_mov_b64_e32 v[144:145], 0
	v_mov_b64_e32 v[114:115], 0
	v_mov_b64_e32 v[116:117], 0
	v_mov_b64_e32 v[118:119], 0
	v_mov_b64_e32 v[120:121], 0
	v_mov_b64_e32 v[146:147], 0
	v_mov_b64_e32 v[148:149], 0
	v_mov_b64_e32 v[150:151], 0
	v_mov_b64_e32 v[152:153], 0
	s_branch .LBB0_745

.LBB0_904:
	s_add_u32 s19, s28, 0x100
	v_mov_b64_e32 v[2:3], 0
	s_addc_u32 s21, s29, 0
	s_mov_b32 s60, -2
	v_mov_b64_e32 v[4:5], 0
	v_mov_b64_e32 v[6:7], 0
	v_mov_b64_e32 v[8:9], 0
	v_mov_b64_e32 v[18:19], 0
	v_mov_b64_e32 v[20:21], 0
	v_mov_b64_e32 v[22:23], 0
	v_mov_b64_e32 v[24:25], 0
	v_mov_b64_e32 v[34:35], 0
	v_mov_b64_e32 v[36:37], 0
	v_mov_b64_e32 v[38:39], 0
	v_mov_b64_e32 v[40:41], 0
	v_mov_b64_e32 v[50:51], 0
	v_mov_b64_e32 v[52:53], 0
	v_mov_b64_e32 v[54:55], 0
	v_mov_b64_e32 v[56:57], 0
	v_mov_b64_e32 v[10:11], 0
	v_mov_b64_e32 v[12:13], 0
	v_mov_b64_e32 v[14:15], 0
	v_mov_b64_e32 v[16:17], 0
	v_mov_b64_e32 v[26:27], 0
	v_mov_b64_e32 v[28:29], 0
	v_mov_b64_e32 v[30:31], 0
	v_mov_b64_e32 v[32:33], 0
	v_mov_b64_e32 v[42:43], 0
	v_mov_b64_e32 v[44:45], 0
	v_mov_b64_e32 v[46:47], 0
	v_mov_b64_e32 v[48:49], 0
	v_mov_b64_e32 v[58:59], 0
	v_mov_b64_e32 v[60:61], 0
	v_mov_b64_e32 v[62:63], 0
	v_mov_b64_e32 v[64:65], 0
	v_mov_b64_e32 v[82:83], 0
	v_mov_b64_e32 v[84:85], 0
	v_mov_b64_e32 v[86:87], 0
	v_mov_b64_e32 v[88:89], 0
	v_mov_b64_e32 v[98:99], 0
	v_mov_b64_e32 v[100:101], 0
	v_mov_b64_e32 v[102:103], 0
	v_mov_b64_e32 v[104:105], 0
	v_mov_b64_e32 v[118:119], 0
	v_mov_b64_e32 v[120:121], 0
	v_mov_b64_e32 v[122:123], 0
	v_mov_b64_e32 v[124:125], 0
	v_mov_b64_e32 v[114:115], 0
	v_mov_b64_e32 v[116:117], 0
	v_mov_b64_e32 v[126:127], 0
	v_mov_b64_e32 v[128:129], 0
	v_mov_b64_e32 v[90:91], 0
	v_mov_b64_e32 v[92:93], 0
	v_mov_b64_e32 v[94:95], 0
	v_mov_b64_e32 v[96:97], 0
	v_mov_b64_e32 v[106:107], 0
	v_mov_b64_e32 v[108:109], 0
	v_mov_b64_e32 v[110:111], 0
	v_mov_b64_e32 v[112:113], 0
	v_mov_b64_e32 v[134:135], 0
	v_mov_b64_e32 v[136:137], 0
	v_mov_b64_e32 v[138:139], 0
	v_mov_b64_e32 v[140:141], 0
	v_mov_b64_e32 v[150:151], 0
	v_mov_b64_e32 v[152:153], 0
	v_mov_b64_e32 v[154:155], 0
	v_mov_b64_e32 v[156:157], 0
